# P2 weight-conversion shares also assigned by the same ticket (ticket<88 -> split-K unit, else conversion share)
# baseline (speedup 1.0000x reference)
.LBB0_435:
	s_andn2_b64 vcc, exec, s[0:1]
	s_cbranch_vccnz .LBB0_515
	s_cmpk_lt_i32 s98, 0x58
	s_cbranch_scc1 .LBB0_515
	s_lshl_b32 s0, s98, 3
	v_readlane_b32 s1, v251, 10
	s_add_i32 s0, s1, s0
	s_addk_i32 s0, 0xfd40
	v_mov_b32_e32 v0, v184
	s_cmpk_gt_i32 s0, 0x48f
	s_cbranch_scc1 .LBB0_515
	v_lshlrev_b32_e32 v1, 2, v0
	s_add_i32 s7, s0, 0x840
	v_ashrrev_i32_e32 v74, 4, v0
	v_and_b32_e32 v75, 60, v1
	s_movk_i32 s0, 0x104
	v_ashrrev_i32_e32 v77, 3, v0
	v_lshlrev_b32_e32 v0, 3, v0
	v_lshlrev_b32_e32 v1, 2, v75
	v_mul_lo_u32 v2, v74, s0
	v_readlane_b32 s0, v251, 26
	v_and_b32_e32 v0, 56, v0
	v_lshlrev_b32_e32 v64, 1, v0
	v_add3_u32 v76, s0, v1, v2
	v_mul_u32_u24_e32 v1, 0x104, v0
	v_lshlrev_b32_e32 v2, 2, v77
	v_add3_u32 v78, s0, v1, v2
	v_readlane_b32 s0, v251, 17
	v_and_b32_e32 v1, 3, v77
	v_mov_b32_e32 v65, 0
	v_readlane_b32 s1, v251, 18
	v_add_u32_e32 v79, 8, v77
	v_add_u32_e32 v80, 16, v77
	v_add_u32_e32 v81, 24, v77
	v_add_u32_e32 v83, 40, v77
	v_add_u32_e32 v84, 48, v77
	v_add_u32_e32 v85, 56, v77
	v_and_or_b32 v1, v2, 16, v1
	v_lshrrev_b32_e32 v2, 1, v77
	v_lshl_add_u64 v[68:69], s[0:1], 0, v[64:65]
	v_readlane_b32 s0, v251, 8
	v_and_or_b32 v86, v2, 12, v1
	v_lshrrev_b32_e32 v2, 1, v79
	v_lshrrev_b32_e32 v3, 1, v80
	v_lshrrev_b32_e32 v4, 1, v81
	v_lshrrev_b32_e32 v5, 1, v83
	v_lshrrev_b32_e32 v6, 1, v84
	v_lshrrev_b32_e32 v7, 1, v85
	v_readlane_b32 s1, v251, 9
	s_add_i32 s6, s56, 0xfffffd40
	v_and_or_b32 v88, v2, 12, v1
	v_and_or_b32 v89, v3, 12, v1
	v_and_or_b32 v90, v4, 12, v1
	v_and_or_b32 v91, v5, 12, v1
	v_and_or_b32 v92, v6, 12, v1
	v_and_or_b32 v93, v7, 12, v1
	v_lshl_add_u64 v[70:71], s[0:1], 0, v[64:65]
	v_lshlrev_b32_e32 v0, 1, v77
	s_lshl_b32 s0, s7, 2
	v_add_u32_e32 v82, 32, v77
	v_or_b32_e32 v87, 0x80, v86
	v_lshl_add_u64 v[66:67], s[52:53], 0, v[64:65]
	v_or_b32_e32 v94, 0x80, v88
	v_or_b32_e32 v95, 0x80, v89
	v_or_b32_e32 v96, 0x80, v90
	v_or_b32_e32 v97, 0x80, v91
	v_or_b32_e32 v98, 0x80, v92
	v_or_b32_e32 v99, 0x80, v93
	s_lshl_b32 s8, s7, 6
	s_lshl_b32 s9, s6, 6
	v_lshl_add_u32 v100, s7, 7, v0
	s_lshl_b32 s10, s6, 7
	s_add_i32 s11, s0, 0x3ea00
	s_lshl_b32 s12, s6, 2
	s_movk_i32 s13, 0x4860
	s_mov_b32 s1, 0
	s_movk_i32 s14, 0xffe0
	s_movk_i32 s15, 0x1600
	s_movk_i32 s16, 0x2c00
	s_branch .LBB0_441
